# scan staging: drop dead per-token decay exp, decay-table reads issued right after the flush barrier, flush address math before the LDS wait; attention: first two PV V-fragment pairs read during the QK
# speedup vs baseline: 1.0225x; 1.0016x over previous
; __device__ __forceinline__ void partialSM(f32x16& p0, f32x16& p1, float& m_reg, float& mn, float& alpha) {
;     constexpr float C = SCALE * 1.4426950408889634f;
;     float pmax = p0[0];
; #pragma unroll
;     for (int r = 1; r < 16; ++r) pmax = fmaxf(pmax, p0[r]);
; #pragma unroll
;     for (int r = 0; r < 16; ++r) pmax = fmaxf(pmax, p1[r]);
;     { auto rr = __builtin_amdgcn_permlane32_swap(__float_as_uint(pmax), __float_as_uint(pmax), false, false);
;       pmax = fmaxf(__uint_as_float(rr[0]), __uint_as_float(rr[1])); }
;     if (__builtin_expect(__all(pmax - m_reg <= THR / SCALE), 1)) { mn = m_reg; alpha = 1.f; }
;     else { mn = fmaxf(m_reg, pmax); alpha = __builtin_amdgcn_exp2f((m_reg - mn) * C); m_reg = mn; }
;     const float mnC = -mn * C;
; #pragma unroll
;     for (int r = 0; r < 16; ++r) p0[r] = __builtin_amdgcn_exp2f(fmaf(p0[r], C, mnC));
; #pragma unroll
;     for (int r = 0; r < 16; ++r) p1[r] = __builtin_amdgcn_exp2f(fmaf(p1[r], C, mnC));
; }
; __device__ __forceinline__ void finishSM(f32x16& p0, f32x16& p1, float alpha, float& l_reg, bf16x8& pa0, bf16x8& pa1, bf16x8& pa2, bf16x8& pa3) {
;     float ps = 0;
; #pragma unroll
;     for (int r = 0; r < 16; ++r) ps += p0[r];
; #pragma unroll
;     for (int r = 0; r < 16; ++r) ps += p1[r];
;     { auto rr = __builtin_amdgcn_permlane32_swap(__float_as_uint(ps), __float_as_uint(ps), false, false);
;       ps = __uint_as_float(rr[0]) + __uint_as_float(rr[1]); }
;     l_reg = l_reg * alpha + ps;
;     ...
;     PK4(p0, 0, pa0); PK4(p0, 8, pa1); PK4(p1, 0, pa2); PK4(p1, 8, pa3);
;     ...
; }
; __device__ __forceinline__ void qkt(f32x16& p0, f32x16& p1, const char* Kn, const char* Kr, const bf16x8* qr, int r32, int hi) {
;     p0 = f32x16{}; p1 = f32x16{};
; #pragma unroll
;     for (int d0 = 0; d0 < 8; ++d0) { const int cb = (d0 * 16 + hi * 8) * 2;
;         const bf16x8 b0 = *reinterpret_cast<const bf16x8*>(Kn + KSWZ(r32, cb));
;         const bf16x8 b1 = *reinterpret_cast<const bf16x8*>(Kn + KSWZ(32 + r32, cb));
;         p0 = __builtin_amdgcn_mfma_f32_32x32x16_bf16(b0, qr[d0], p0, 0, 0, 0);
;         p1 = __builtin_amdgcn_mfma_f32_32x32x16_bf16(b1, qr[d0], p1, 0, 0, 0); }
; #pragma unroll
;     for (int d0 = 0; d0 < 4; ++d0) { const int cb = (d0 * 16 + hi * 8) * 2;
;         const bf16x8 b0 = *reinterpret_cast<const bf16x8*>(Kr + KSWZ(r32, cb));
.LBB0_60:
	s_and_b32 s16, s23, 0x4000
	s_add_i32 s2, s16, 0
	s_add_i32 s3, s2, 0x10000
	v_add_u32_e32 v0, s2, v221
	ds_read_b128 v[66:69], v0 offset:32768
	ds_read_b128 v[70:73], v0 offset:40960
	v_add_u32_e32 v0, s2, v222
	ds_read_b128 v[232:235], v0 offset:32768
	ds_read_b128 v[236:239], v0 offset:40960
	v_add_u32_e32 v0, s2, v223
	ds_read_b128 v[240:243], v0 offset:32768
	ds_read_b128 v[244:247], v0 offset:40960
	v_add_u32_e32 v0, s2, v224
	ds_read_b128 v[206:209], v0 offset:32768
	ds_read_b128 v[210:213], v0 offset:40960
	s_waitcnt lgkmcnt(7)
	v_mfma_f32_32x32x16_bf16 v[82:97], v[66:69], v[98:101], 0
	s_waitcnt lgkmcnt(6)
	v_mfma_f32_32x32x16_bf16 v[66:81], v[70:73], v[98:101], 0
	s_waitcnt lgkmcnt(5)
	v_mfma_f32_32x32x16_bf16 v[82:97], v[232:235], v[102:105], v[82:97]
	s_waitcnt lgkmcnt(4)
	v_mfma_f32_32x32x16_bf16 v[66:81], v[236:239], v[102:105], v[66:81]
	v_add3_u32 v0, s2, v225, v220
	ds_read_b128 v[232:235], v0 offset:32768
	ds_read_b128 v[236:239], v0 offset:40960
	s_waitcnt lgkmcnt(5)
	v_mfma_f32_32x32x16_bf16 v[82:97], v[240:243], v[106:109], v[82:97]
	s_waitcnt lgkmcnt(4)
	v_mfma_f32_32x32x16_bf16 v[66:81], v[244:247], v[106:109], v[66:81]
	v_add3_u32 v0, s2, v226, v220
	ds_read_b128 v[240:243], v0 offset:32768
	ds_read_b128 v[244:247], v0 offset:40960
	s_waitcnt lgkmcnt(5)
	v_mfma_f32_32x32x16_bf16 v[82:97], v[206:209], v[110:113], v[82:97]
	s_waitcnt lgkmcnt(4)
	v_mfma_f32_32x32x16_bf16 v[66:81], v[210:213], v[110:113], v[66:81]
	v_add3_u32 v0, s2, v227, v220
	ds_read_b128 v[206:209], v0 offset:32768
	ds_read_b128 v[210:213], v0 offset:40960
	s_waitcnt lgkmcnt(5)
	v_mfma_f32_32x32x16_bf16 v[82:97], v[232:235], v[114:117], v[82:97]
	s_waitcnt lgkmcnt(4)
	v_mfma_f32_32x32x16_bf16 v[66:81], v[236:239], v[114:117], v[66:81]
	v_add3_u32 v0, s2, v228, v220
	ds_read_b128 v[232:235], v0 offset:32768
	ds_read_b128 v[236:239], v0 offset:40960
	s_waitcnt lgkmcnt(5)
	v_mfma_f32_32x32x16_bf16 v[82:97], v[240:243], v[118:121], v[82:97]
	s_waitcnt lgkmcnt(4)
	v_mfma_f32_32x32x16_bf16 v[66:81], v[244:247], v[118:121], v[66:81]
	v_add_u32_e32 v0, s3, v221
	ds_read_b128 v[240:243], v0 offset:0
	ds_read_b128 v[244:247], v0 offset:8192
	s_waitcnt lgkmcnt(5)
	v_mfma_f32_32x32x16_bf16 v[82:97], v[206:209], v[122:125], v[82:97]
	s_waitcnt lgkmcnt(4)
	v_mfma_f32_32x32x16_bf16 v[66:81], v[210:213], v[122:125], v[66:81]
	v_add_u32_e32 v0, s3, v222
	ds_read_b128 v[206:209], v0 offset:0
	ds_read_b128 v[210:213], v0 offset:8192
	s_waitcnt lgkmcnt(5)
	v_mfma_f32_32x32x16_bf16 v[82:97], v[232:235], v[126:129], v[82:97]
	s_waitcnt lgkmcnt(4)
	v_mfma_f32_32x32x16_bf16 v[66:81], v[236:239], v[126:129], v[66:81]
	v_add_u32_e32 v0, s3, v223
	ds_read_b128 v[232:235], v0 offset:0
	ds_read_b128 v[236:239], v0 offset:8192
	s_waitcnt lgkmcnt(5)
	v_mfma_f32_32x32x16_bf16 v[82:97], v[240:243], v[130:133], v[82:97]
	s_waitcnt lgkmcnt(4)
	v_mfma_f32_32x32x16_bf16 v[66:81], v[244:247], v[130:133], v[66:81]
	v_add_u32_e32 v0, s3, v224
	ds_read_b128 v[240:243], v0 offset:0
	ds_read_b128 v[244:247], v0 offset:8192
	s_waitcnt lgkmcnt(5)
	v_mfma_f32_32x32x16_bf16 v[82:97], v[206:209], v[134:137], v[82:97]
	s_waitcnt lgkmcnt(4)
	v_mfma_f32_32x32x16_bf16 v[66:81], v[210:213], v[134:137], v[66:81]
	v_add_u32_e32 v248, s16, v230
	ds_read_b64_tr_b16 v[206:207], v248 offset:0x0
	ds_read_b64_tr_b16 v[208:209], v248 offset:0x800
	ds_read_b64_tr_b16 v[210:211], v248 offset:0x1000
	ds_read_b64_tr_b16 v[212:213], v248 offset:0x1800
	s_waitcnt lgkmcnt(7)
	v_mfma_f32_32x32x16_bf16 v[82:97], v[232:235], v[138:141], v[82:97]
	s_waitcnt lgkmcnt(6)
	v_mfma_f32_32x32x16_bf16 v[66:81], v[236:239], v[138:141], v[66:81]
	s_waitcnt lgkmcnt(5)
	v_mfma_f32_32x32x16_bf16 v[82:97], v[240:243], v[142:145], v[82:97]
	s_waitcnt lgkmcnt(4)
	v_mfma_f32_32x32x16_bf16 v[66:81], v[244:247], v[142:145], v[66:81]
	s_mov_b32 s2, 0x42ddb3d8
	s_nop 9
	v_max_f32_e32 v0, v83, v83
	v_max_f32_e32 v202, v82, v82
	v_max_f32_e32 v0, v202, v0
	v_max3_f32 v0, v0, v84, v85
	v_max3_f32 v0, v0, v86, v87
	v_max3_f32 v0, v0, v88, v89
	v_max3_f32 v0, v0, v90, v91
	v_max3_f32 v0, v0, v92, v93
	v_max3_f32 v0, v0, v94, v95
	v_max3_f32 v0, v0, v96, v97
	v_max3_f32 v0, v0, v66, v67
	v_max3_f32 v0, v0, v68, v69
	v_max3_f32 v0, v0, v70, v71
	v_max3_f32 v0, v0, v72, v73
	v_max3_f32 v0, v0, v74, v75
	v_max3_f32 v0, v0, v76, v77
	v_max3_f32 v0, v0, v78, v79
	v_max3_f32 v0, v0, v80, v81
	v_mov_b32_e32 v202, v0
	s_nop 1
	v_permlane32_swap_b32_e32 v0, v202
	v_max_f32_e32 v202, v202, v202
	v_max_f32_e32 v0, v0, v0
	v_max_f32_e32 v0, v0, v202
	v_sub_f32_e32 v202, v0, v183
	v_cmp_ge_f32_e32 vcc, s2, v202
	s_cmp_eq_u64 vcc, exec
	v_max_f32_e32 v202, v183, v183
	s_cselect_b64 vcc, -1, 0
	v_max_f32_e32 v202, v202, v0
	v_sub_f32_e32 v0, v183, v202
	v_cndmask_b32_e32 v183, v202, v183, vcc
	v_mul_f32_e32 v202, 0xbdd53b94, v183
	v_fmamk_f32 v82, v82, 0x3dd53b94, v202
	v_fmamk_f32 v83, v83, 0x3dd53b94, v202
	v_fmamk_f32 v84, v84, 0x3dd53b94, v202
	v_fmamk_f32 v85, v85, 0x3dd53b94, v202
	v_fmamk_f32 v86, v86, 0x3dd53b94, v202
	v_fmamk_f32 v87, v87, 0x3dd53b94, v202
	v_fmamk_f32 v88, v88, 0x3dd53b94, v202
	v_fmamk_f32 v89, v89, 0x3dd53b94, v202
	v_exp_f32_e32 v82, v82
	v_exp_f32_e32 v83, v83
	v_exp_f32_e32 v84, v84
	v_exp_f32_e32 v85, v85
	v_exp_f32_e32 v86, v86
	v_exp_f32_e32 v87, v87
	v_exp_f32_e32 v88, v88
	v_exp_f32_e32 v89, v89
	v_fmamk_f32 v90, v90, 0x3dd53b94, v202
	v_fmamk_f32 v91, v91, 0x3dd53b94, v202
	v_fmamk_f32 v92, v92, 0x3dd53b94, v202
	v_fmamk_f32 v93, v93, 0x3dd53b94, v202
	v_fmamk_f32 v94, v94, 0x3dd53b94, v202
	v_fmamk_f32 v95, v95, 0x3dd53b94, v202
	v_fmamk_f32 v96, v96, 0x3dd53b94, v202
	v_fmamk_f32 v97, v97, 0x3dd53b94, v202
	v_mul_f32_e32 v0, 0x3dd53b94, v0
	v_exp_f32_e32 v90, v90
	v_add_f32_e32 v240, v82, v83
	v_exp_f32_e32 v91, v91
	v_add_f32_e32 v241, v84, v85
	v_exp_f32_e32 v92, v92
	v_add_f32_e32 v240, v86, v240
	v_exp_f32_e32 v93, v93
	v_add_f32_e32 v241, v87, v241
	v_exp_f32_e32 v94, v94
	v_add_f32_e32 v240, v88, v240
	v_exp_f32_e32 v95, v95
	v_add_f32_e32 v241, v89, v241
	v_exp_f32_e32 v96, v96
	v_exp_f32_e32 v97, v97
	v_exp_f32_e32 v0, v0
	v_add_f32_e32 v240, v90, v240
	v_add_f32_e32 v241, v91, v241
	v_add_f32_e32 v240, v92, v240
	v_add_f32_e32 v241, v93, v241
	v_add_f32_e32 v240, v94, v240
	v_add_f32_e32 v241, v95, v241
	v_add_f32_e32 v240, v96, v240
	v_add_f32_e32 v241, v97, v241
	v_cndmask_b32_e64 v0, v0, 1.0, vcc
	v_cvt_pk_bf16_f32 v244, v82, v83
	v_cvt_pk_bf16_f32 v245, v84, v85
	v_cvt_pk_bf16_f32 v246, v86, v87
	v_cvt_pk_bf16_f32 v247, v88, v89
	v_cvt_pk_bf16_f32 v248, v90, v91
	v_cvt_pk_bf16_f32 v249, v92, v93
	v_cvt_pk_bf16_f32 v250, v94, v95
	v_cvt_pk_bf16_f32 v251, v96, v97
	s_nop 1
	v_permlane32_swap_b32_e32 v244, v246
	v_permlane32_swap_b32_e32 v245, v247
	v_permlane32_swap_b32_e32 v248, v250
	v_permlane32_swap_b32_e32 v249, v251
	v_cmp_gt_f32_e32 vcc, 1.0, v0
	s_cbranch_vccz .LBB0_64
	s_and_saveexec_b64 s[2:3], s[6:7]
	ds_write_b32 v229, v0 offset:128
	s_or_b64 exec, exec, s[2:3]
	s_waitcnt lgkmcnt(0)
	v_add_u32_e32 v96, v167, v219
	ds_read_b128 v[84:87], v96 offset:224
	ds_read_b128 v[88:91], v96 offset:192
	ds_read_b128 v[92:95], v96 offset:160
	ds_read_b128 v[232:235], v96 offset:128
	s_waitcnt lgkmcnt(3)
	v_pk_mul_f32 v[62:63], v[62:63], v[84:85]
	s_waitcnt lgkmcnt(2)
	v_pk_mul_f32 v[58:59], v[58:59], v[88:89]
	s_waitcnt lgkmcnt(1)
	v_pk_mul_f32 v[54:55], v[54:55], v[92:93]
	v_pk_mul_f32 v[64:65], v[64:65], v[86:87]
	v_pk_mul_f32 v[60:61], v[60:61], v[90:91]
	v_pk_mul_f32 v[56:57], v[56:57], v[94:95]
	s_waitcnt lgkmcnt(0)
	v_pk_mul_f32 v[52:53], v[52:53], v[234:235]
	v_pk_mul_f32 v[50:51], v[50:51], v[232:233]
	v_pk_mul_f32 v[46:47], v[46:47], v[84:85]
	v_pk_mul_f32 v[42:43], v[42:43], v[88:89]
	v_pk_mul_f32 v[38:39], v[38:39], v[92:93]
	v_pk_mul_f32 v[48:49], v[48:49], v[86:87]
	v_pk_mul_f32 v[44:45], v[44:45], v[90:91]
	v_pk_mul_f32 v[40:41], v[40:41], v[94:95]
	v_pk_mul_f32 v[36:37], v[36:37], v[234:235]
	v_pk_mul_f32 v[34:35], v[34:35], v[232:233]
	v_pk_mul_f32 v[30:31], v[30:31], v[84:85]
	v_pk_mul_f32 v[26:27], v[26:27], v[88:89]
	v_pk_mul_f32 v[22:23], v[22:23], v[92:93]
	v_pk_mul_f32 v[32:33], v[32:33], v[86:87]
	v_pk_mul_f32 v[28:29], v[28:29], v[90:91]
	v_pk_mul_f32 v[24:25], v[24:25], v[94:95]
	v_pk_mul_f32 v[20:21], v[20:21], v[234:235]
	v_pk_mul_f32 v[18:19], v[18:19], v[232:233]
	v_pk_mul_f32 v[14:15], v[14:15], v[84:85]
	v_pk_mul_f32 v[10:11], v[10:11], v[88:89]
	v_pk_mul_f32 v[6:7], v[6:7], v[92:93]
	v_pk_mul_f32 v[16:17], v[16:17], v[86:87]
	v_pk_mul_f32 v[12:13], v[12:13], v[90:91]
	v_pk_mul_f32 v[8:9], v[8:9], v[94:95]
	v_pk_mul_f32 v[4:5], v[4:5], v[234:235]
	v_pk_mul_f32 v[2:3], v[2:3], v[232:233]
; __device__ __forceinline__ void partialSM(f32x16& p0, f32x16& p1, float& m_reg, float& mn, float& alpha) {
;     ...
;     for (int r = 0; r < 16; ++r) p0[r] = __builtin_amdgcn_exp2f(fmaf(p0[r], C, mnC));
; #pragma unroll
;     for (int r = 0; r < 16; ++r) p1[r] = __builtin_amdgcn_exp2f(fmaf(p1[r], C, mnC));
; }
; __device__ __forceinline__ void finishSM(f32x16& p0, f32x16& p1, float alpha, float& l_reg, bf16x8& pa0, bf16x8& pa1, bf16x8& pa2, bf16x8& pa3) {
;     float ps = 0;
; #pragma unroll
;     for (int r = 0; r < 16; ++r) ps += p0[r];
; #pragma unroll
;     for (int r = 0; r < 16; ++r) ps += p1[r];
;     { auto rr = __builtin_amdgcn_permlane32_swap(__float_as_uint(ps), __float_as_uint(ps), false, false);
;       ps = __uint_as_float(rr[0]) + __uint_as_float(rr[1]); }
;     l_reg = l_reg * alpha + ps;
;     ...
;     PK4(p0, 0, pa0); PK4(p0, 8, pa1); PK4(p1, 0, pa2); PK4(p1, 8, pa3);
;     ...
; }
; __device__ __forceinline__ void qkt(f32x16& p0, f32x16& p1, const char* Kn, const char* Kr, const bf16x8* qr, int r32, int hi) {
;     p0 = f32x16{}; p1 = f32x16{};
; #pragma unroll
;     for (int d0 = 0; d0 < 8; ++d0) { const int cb = (d0 * 16 + hi * 8) * 2;
;         const bf16x8 b0 = *reinterpret_cast<const bf16x8*>(Kn + KSWZ(r32, cb));
;         const bf16x8 b1 = *reinterpret_cast<const bf16x8*>(Kn + KSWZ(32 + r32, cb));
;         p0 = __builtin_amdgcn_mfma_f32_32x32x16_bf16(b0, qr[d0], p0, 0, 0, 0);
;         p1 = __builtin_amdgcn_mfma_f32_32x32x16_bf16(b1, qr[d0], p1, 0, 0, 0); }
; #pragma unroll
;     for (int d0 = 0; d0 < 4; ++d0) { const int cb = (d0 * 16 + hi * 8) * 2;
;         const bf16x8 b0 = *reinterpret_cast<const bf16x8*>(Kr + KSWZ(r32, cb));
;         const bf16x8 b1 = *reinterpret_cast<const bf16x8*>(Kr + KSWZ(32 + r32, cb));
;         p0 = __builtin_amdgcn_mfma_f32_32x32x16_bf16(b0, qr[8 + d0], p0, 0, 0, 0);
;         p1 = __builtin_amdgcn_mfma_f32_32x32x16_bf16(b1, qr[8 + d0], p1, 0, 0, 0); }
; }
; __device__ __forceinline__ int v_st(int k, int c) { const int kk = (k & ~0xC) | ((k & 4) << 1) | ((k & 8) >> 1); return ((kk >> 3) * 4 + (c >> 5)) * 512 + ((kk & 7) * 32 + (c & 31)) * 2; }
; __device__ __forceinline__ int v_rd_base(int lane) { return ((lane & 3) << 3) | (((lane >> 2) & 3) << 6) | (((lane >> 4) & 1) << 5) | (((lane >> 5) & 1) << 8); }
; template <int OFF> __device__ __forceinline__ s16x4 tr_read(int vb) {
.LBB0_64:
	v_add_u32_e32 v96, s16, v230
	ds_read_b64_tr_b16 v[92:93], v96 offset:0x200
	ds_read_b64_tr_b16 v[94:95], v96 offset:0xa00
	ds_read_b64_tr_b16 v[232:233], v96 offset:0x1200
	ds_read_b64_tr_b16 v[234:235], v96 offset:0x1a00
	s_waitcnt lgkmcnt(6)
	v_mfma_f32_32x32x16_bf16 v[50:65], v[244:247], v[206:209], v[50:65]
	ds_read_b64_tr_b16 v[84:85], v96 offset:0x400
	ds_read_b64_tr_b16 v[86:87], v96 offset:0xc00
	v_fmamk_f32 v66, v66, 0x3dd53b94, v202
	v_fmamk_f32 v67, v67, 0x3dd53b94, v202
	v_fmamk_f32 v68, v68, 0x3dd53b94, v202
	v_fmamk_f32 v69, v69, 0x3dd53b94, v202
	v_fmamk_f32 v70, v70, 0x3dd53b94, v202
	v_fmamk_f32 v71, v71, 0x3dd53b94, v202
	v_fmamk_f32 v72, v72, 0x3dd53b94, v202
	v_fmamk_f32 v73, v73, 0x3dd53b94, v202
	s_waitcnt lgkmcnt(6)
	v_mfma_f32_32x32x16_bf16 v[50:65], v[248:251], v[210:213], v[50:65]
	ds_read_b64_tr_b16 v[88:89], v96 offset:0x1400
	ds_read_b64_tr_b16 v[90:91], v96 offset:0x1c00
	v_exp_f32_e32 v66, v66
	v_exp_f32_e32 v67, v67
	v_exp_f32_e32 v68, v68
	v_exp_f32_e32 v69, v69
	v_exp_f32_e32 v70, v70
	v_exp_f32_e32 v71, v71
	v_exp_f32_e32 v72, v72
	v_exp_f32_e32 v73, v73
	s_waitcnt lgkmcnt(6)
	v_mfma_f32_32x32x16_bf16 v[34:49], v[244:247], v[92:95], v[34:49]
	ds_read_b64_tr_b16 v[92:93], v96 offset:0x600
	ds_read_b64_tr_b16 v[94:95], v96 offset:0xe00
	v_fmamk_f32 v74, v74, 0x3dd53b94, v202
	v_fmamk_f32 v75, v75, 0x3dd53b94, v202
	v_fmamk_f32 v76, v76, 0x3dd53b94, v202
	v_fmamk_f32 v77, v77, 0x3dd53b94, v202
	v_fmamk_f32 v78, v78, 0x3dd53b94, v202
	v_fmamk_f32 v79, v79, 0x3dd53b94, v202
	v_fmamk_f32 v80, v80, 0x3dd53b94, v202
	v_fmamk_f32 v81, v81, 0x3dd53b94, v202
	s_waitcnt lgkmcnt(6)
	v_mfma_f32_32x32x16_bf16 v[34:49], v[248:251], v[232:235], v[34:49]
	ds_read_b64_tr_b16 v[232:233], v96 offset:0x1600
	ds_read_b64_tr_b16 v[234:235], v96 offset:0x1e00
	v_exp_f32_e32 v74, v74
	v_add_f32_e32 v242, v66, v67
	v_exp_f32_e32 v75, v75
	v_add_f32_e32 v243, v68, v69
	v_exp_f32_e32 v76, v76
	v_add_f32_e32 v242, v70, v242
	v_exp_f32_e32 v77, v77
	v_add_f32_e32 v243, v71, v243
	s_waitcnt lgkmcnt(6)
	v_mfma_f32_32x32x16_bf16 v[18:33], v[244:247], v[84:87], v[18:33]
	ds_read_b64_tr_b16 v[84:85], v96 offset:0x2000
	ds_read_b64_tr_b16 v[86:87], v96 offset:0x2800
	v_exp_f32_e32 v78, v78
	v_add_f32_e32 v242, v72, v242
	v_exp_f32_e32 v79, v79
	v_add_f32_e32 v243, v73, v243
	v_exp_f32_e32 v80, v80
	v_exp_f32_e32 v81, v81
	v_add_f32_e32 v242, v74, v242
	v_add_f32_e32 v243, v75, v243
	s_waitcnt lgkmcnt(6)
	v_mfma_f32_32x32x16_bf16 v[18:33], v[248:251], v[88:91], v[18:33]
	ds_read_b64_tr_b16 v[88:89], v96 offset:0x3000
	ds_read_b64_tr_b16 v[90:91], v96 offset:0x3800
	v_add_f32_e32 v242, v76, v242
	v_add_f32_e32 v243, v77, v243
	v_add_f32_e32 v242, v78, v242
	v_add_f32_e32 v243, v79, v243
	v_add_f32_e32 v242, v80, v242
	v_add_f32_e32 v243, v81, v243
	v_add_f32_e32 v240, v240, v241
	v_add_f32_e32 v242, v242, v243
	s_waitcnt lgkmcnt(6)
	v_mfma_f32_32x32x16_bf16 v[2:17], v[244:247], v[92:95], v[2:17]
	ds_read_b64_tr_b16 v[92:93], v96 offset:0x2200
	ds_read_b64_tr_b16 v[94:95], v96 offset:0x2a00
	v_cvt_pk_bf16_f32 v66, v66, v67
	v_cvt_pk_bf16_f32 v67, v68, v69
	v_cvt_pk_bf16_f32 v68, v70, v71
	v_cvt_pk_bf16_f32 v69, v72, v73
	v_cvt_pk_bf16_f32 v70, v74, v75
	v_cvt_pk_bf16_f32 v71, v76, v77
	v_cvt_pk_bf16_f32 v72, v78, v79
	v_cvt_pk_bf16_f32 v73, v80, v81
	s_waitcnt lgkmcnt(6)
	v_mfma_f32_32x32x16_bf16 v[2:17], v[248:251], v[232:235], v[2:17]
	ds_read_b64_tr_b16 v[232:233], v96 offset:0x3200
	ds_read_b64_tr_b16 v[234:235], v96 offset:0x3a00
	v_add_f32_e32 v82, v240, v242
	s_nop 0
	v_mov_b32_e32 v83, v82
	v_permlane32_swap_b32_e32 v66, v68
	v_permlane32_swap_b32_e32 v67, v69
	v_permlane32_swap_b32_e32 v70, v72
	v_permlane32_swap_b32_e32 v71, v73
	v_permlane32_swap_b32_e32 v82, v83
	s_waitcnt lgkmcnt(6)
	v_mfma_f32_32x32x16_bf16 v[50:65], v[66:69], v[84:87], v[50:65]
	ds_read_b64_tr_b16 v[84:85], v96 offset:0x2400
	ds_read_b64_tr_b16 v[86:87], v96 offset:0x2c00
	s_waitcnt lgkmcnt(6)
	v_mfma_f32_32x32x16_bf16 v[50:65], v[70:73], v[88:91], v[50:65]
	ds_read_b64_tr_b16 v[88:89], v96 offset:0x3400
	ds_read_b64_tr_b16 v[90:91], v96 offset:0x3c00
	s_waitcnt lgkmcnt(6)
	v_mfma_f32_32x32x16_bf16 v[34:49], v[66:69], v[92:95], v[34:49]
	ds_read_b64_tr_b16 v[92:93], v96 offset:0x2600
	ds_read_b64_tr_b16 v[94:95], v96 offset:0x2e00
	s_waitcnt lgkmcnt(6)
	v_mfma_f32_32x32x16_bf16 v[34:49], v[70:73], v[232:235], v[34:49]
	ds_read_b64_tr_b16 v[232:233], v96 offset:0x3600
	ds_read_b64_tr_b16 v[234:235], v96 offset:0x3e00
	s_waitcnt lgkmcnt(6)
	v_mfma_f32_32x32x16_bf16 v[18:33], v[66:69], v[84:87], v[18:33]
	s_waitcnt lgkmcnt(4)
	v_mfma_f32_32x32x16_bf16 v[18:33], v[70:73], v[88:91], v[18:33]
	s_waitcnt lgkmcnt(2)
	s_andn2_b64 vcc, exec, s[14:15]
	v_mfma_f32_32x32x16_bf16 v[2:17], v[66:69], v[92:95], v[2:17]
	s_waitcnt lgkmcnt(0)
	v_mfma_f32_32x32x16_bf16 v[2:17], v[70:73], v[232:235], v[2:17]
	s_cbranch_vccnz .LBB0_66
	s_xor_b32 s2, s16, 0x4000
	s_add_i32 s3, s2, 0
	v_add_u32_e32 v66, s3, v195
	s_waitcnt vmcnt(4)
	ds_write_b128 v66, v[146:149]
	v_add_u32_e32 v66, s3, v196
	s_waitcnt vmcnt(2)
	ds_write_b128 v66, v[154:157]
	v_add_u32_e32 v66, s3, v197
	ds_write_b128 v66, v[150:153] offset:32768
	v_add_u32_e32 v66, s3, v198
	s_waitcnt vmcnt(1)
	ds_write_b128 v66, v[158:161] offset:32768
	v_add_u32_e32 v66, s2, v199
	s_waitcnt vmcnt(0)
	ds_write_b128 v66, v[162:165]

.LBB0_191:
	s_or_b64 exec, exec, s[0:1]
	v_add_f32_e32 v0, v0, v61
	v_max_f32_e32 v0, 0x179abe15, v0
	v_rsq_f32_e32 v0, v0
	v_rcp_f32_e32 v70, v66
	v_rcp_f32_e32 v71, v67
	v_rcp_f32_e32 v72, v68
	v_rcp_f32_e32 v73, v69
	s_bitcmp1_b32 s2, 0
	s_cselect_b32 s0, 0xc000, 0
	v_pk_mul_f32 v[50:51], v[50:51], v[0:1] op_sel_hi:[1,0] neg_lo:[0,1] neg_hi:[0,1]
	v_pk_mul_f32 v[48:49], v[48:49], v[0:1] op_sel_hi:[1,0] neg_lo:[0,1] neg_hi:[0,1]
	v_pk_mul_f32 v[14:15], v[14:15], v[66:67]
	v_pk_mul_f32 v[16:17], v[16:17], v[68:69]
	v_pk_mul_f32 v[46:47], v[46:47], v[50:51] neg_lo:[0,1] neg_hi:[0,1]
	v_pk_mul_f32 v[44:45], v[44:45], v[48:49] neg_lo:[0,1] neg_hi:[0,1]
	v_pk_mul_f32 v[18:19], v[18:19], v[70:71]
	v_pk_mul_f32 v[20:21], v[20:21], v[72:73]
	v_pk_mul_f32 v[48:49], v[48:49], v[74:75]
	v_pk_mul_f32 v[50:51], v[50:51], v[76:77]
	v_add_u32_e32 v0, s0, v55
	v_pk_mul_f32 v[44:45], v[44:45], v[70:71]
	v_pk_mul_f32 v[46:47], v[46:47], v[72:73]
	ds_write_b128 v0, v[66:69]
	ds_write_b128 v0, v[18:21] offset:256
	ds_write_b128 v0, v[48:51] offset:512
	ds_write_b128 v0, v[44:47] offset:768
	ds_write_b128 v0, v[14:17] offset:1024
	v_lshlrev_b32_e32 v14, 16, v26
	v_and_b32_e32 v15, 0xffff0000, v26
	v_lshlrev_b32_e32 v16, 16, v27
	v_and_b32_e32 v17, 0xffff0000, v27
	ds_write_b128 v0, v[14:17] offset:1280

; #define LAS __attribute__((address_space(3)))
; __device__ __forceinline__ unsigned cvt_pk_f16(float lo, float hi) { _Float16 a = (_Float16)lo, b = (_Float16)hi; return (unsigned)__builtin_bit_cast(unsigned short, a) | ((unsigned)__builtin_bit_cast(unsigned short, b) << 16); }
; __device__ __forceinline__ void scan_phase(const KP& P, LAS unsigned char* lds, const int tid, const int bx, const int G) {
;     ...
;             __syncthreads();
;             {
;                 const f32x4 y4 = *(const LAS f32x4*)(ybuf + tk * 64 + cg * 4);
;                 u32x2 w; w.x = cvt_pk_f16(y4.x, y4.y); w.y = cvt_pk_f16(y4.z, y4.w);
;                 *(u32x2*)(Yd + (size_t)scan_row(c, tk, d, b) * D + ch) = w;
;             }
;             if (c + 1 < NCH) SC_WRITE((c + 1) & 1, c + 1);
.LBB0_229:
	s_waitcnt lgkmcnt(0)
	s_barrier
	v_lshl_add_u32 v66, v52, 8, v57
	ds_read_b128 v[14:17], v66
	ds_read_b128 v[62:65], v66 offset:256
	ds_read_b128 v[66:69], v57 offset:16384
	ds_read_b128 v[74:77], v57 offset:24576
	s_cmp_lt_u32 s3, 8
	s_cselect_b64 vcc, -1, 0
	s_and_b64 s[0:1], vcc, exec
	s_cselect_b32 s0, 0xff, s80
	s_cselect_b32 s1, s31, s33
	v_lshl_add_u32 v70, s3, 5, v52
	v_add_u32_e32 v71, 0xffffff00, v70
	v_cndmask_b32_e32 v71, v71, v70, vcc
	v_sub_u32_e32 v70, s0, v70
	v_cndmask_b32_e64 v70, v70, v71, s[12:13]
	v_add_u32_e32 v70, s1, v70
	v_ashrrev_i32_e32 v71, 31, v70
	v_lshlrev_b64 v[70:71], 12, v[70:71]
	v_lshl_add_u64 v[70:71], v[32:33], 0, v[70:71]
	s_waitcnt lgkmcnt(0)
	v_pk_add_f32 v[14:15], v[14:15], v[62:63]
	v_pk_add_f32 v[16:17], v[16:17], v[64:65]
	v_cvt_f16_f32_e32 v0, v14
	v_cvt_f16_f32_sdwa v14, v15 dst_sel:WORD_1 dst_unused:UNUSED_PAD src0_sel:DWORD
	v_cvt_f16_f32_e32 v15, v16
	v_cvt_f16_f32_sdwa v16, v17 dst_sel:WORD_1 dst_unused:UNUSED_PAD src0_sel:DWORD
	v_or_b32_e32 v14, v14, v0
	v_or_b32_e32 v15, v16, v15
	s_and_b64 vcc, exec, s[4:5]
	global_store_dwordx2 v[70:71], v[14:15], off
	s_cbranch_vccz .LBB0_192
	s_waitcnt vmcnt(1)
	v_cvt_f32_f16_sdwa v45, v30 dst_sel:DWORD dst_unused:UNUSED_PAD src0_sel:WORD_1
	v_cvt_f32_f16_e32 v44, v30
	v_cvt_f32_f16_sdwa v47, v31 dst_sel:DWORD dst_unused:UNUSED_PAD src0_sel:WORD_1
	v_cvt_f32_f16_e32 v46, v31
	v_lshlrev_b32_e32 v14, 16, v24
	v_pk_add_f32 v[18:19], v[44:45], -1.0 op_sel_hi:[1,0]
	v_and_b32_e32 v15, 0xffff0000, v24
	v_pk_add_f32 v[20:21], v[46:47], -1.0 op_sel_hi:[1,0]
	v_lshlrev_b32_e32 v16, 16, v25
	v_and_b32_e32 v17, 0xffff0000, v25
	v_pk_fma_f32 v[20:21], v[8:9], v[20:21], 1.0 op_sel_hi:[1,1,0]
	v_pk_fma_f32 v[18:19], v[6:7], v[18:19], 1.0 op_sel_hi:[1,1,0]
	v_pk_mul_f32 v[50:51], v[4:5], v[16:17]
	v_pk_mul_f32 v[48:49], v[2:3], v[14:15]
	v_pk_mul_f32 v[20:21], v[20:21], v[16:17]
	v_pk_mul_f32 v[18:19], v[18:19], v[14:15]
	v_lshlrev_b32_e32 v14, 16, v22
	v_and_b32_e32 v15, 0xffff0000, v22
	v_lshlrev_b32_e32 v16, 16, v23
	v_and_b32_e32 v17, 0xffff0000, v23
	v_pk_mul_f32 v[62:63], v[18:19], v[14:15]
	v_pk_mul_f32 v[64:65], v[20:21], v[16:17]
	v_mul_f32_e32 v0, v49, v49
	v_mul_f32_e32 v61, v51, v51
	v_pk_mul_f32 v[64:65], v[12:13], v[64:65]
	v_pk_mul_f32 v[62:63], v[10:11], v[62:63]
	v_fmac_f32_e32 v0, v48, v48
	v_fmac_f32_e32 v61, v50, v50
	v_add_f32_e32 v0, v0, v61
	v_add_f32_e32 v61, v62, v63
	v_add_f32_e32 v62, v64, v65
	v_add_f32_e32 v62, v61, v62
	v_add_f32_dpp v0, v0, v0 quad_perm:[1,0,3,2] row_mask:0xf bank_mask:0xf bound_ctrl:1
	s_nop 0
	v_add_f32_dpp v62, v62, v62 quad_perm:[1,0,3,2] row_mask:0xf bank_mask:0xf bound_ctrl:1
	v_add_f32_dpp v0, v0, v0 quad_perm:[2,3,0,1] row_mask:0xf bank_mask:0xf bound_ctrl:1
	s_nop 0
	v_add_f32_dpp v62, v62, v62 quad_perm:[2,3,0,1] row_mask:0xf bank_mask:0xf bound_ctrl:1
	v_add_f32_dpp v0, v0, v0 row_half_mirror row_mask:0xf bank_mask:0xf bound_ctrl:1
	s_nop 0
	v_add_f32_dpp v62, v62, v62 row_half_mirror row_mask:0xf bank_mask:0xf bound_ctrl:1
	v_mov_b32_dpp v61, v0 row_mirror row_mask:0xf bank_mask:0xf bound_ctrl:1
	s_nop 0
	v_mov_b32_dpp v63, v62 row_mirror row_mask:0xf bank_mask:0xf bound_ctrl:1
	s_and_saveexec_b64 s[0:1], s[6:7]
	s_cbranch_execz .LBB0_191
	s_cmp_lt_u32 s3, 7
	s_cselect_b64 vcc, -1, 0
	v_add_f32_e32 v64, v62, v63
	v_lshl_add_u32 v62, s2, 5, v52
	s_and_b64 s[4:5], vcc, exec
	v_add_u32_e32 v63, 0xffffff00, v62
	s_cselect_b32 s3, 0xff, s80
	v_cndmask_b32_e32 v63, v63, v62, vcc
	v_sub_u32_e32 v62, s3, v62
	s_cselect_b32 s4, s31, s33
	v_cndmask_b32_e64 v62, v62, v63, s[12:13]
	v_add_u32_e32 v62, s4, v62
	v_ashrrev_i32_e32 v63, 31, v62
	v_lshlrev_b64 v[62:63], 7, v[62:63]
	v_lshl_add_u64 v[62:63], v[34:35], 0, v[62:63]
	global_store_dword v[62:63], v64, off
	s_branch .LBB0_191
